# v10: RG-LRU conv loop runs nvalid steps (8 for sample units) instead of 64; on top of v9
# speedup vs baseline: 1.0418x; 1.0051x over previous
; DI float bf2f(unsigned v) { return __uint_as_float(v << 16); }
; DI bf16_t f2bf(float f) { return (bf16_t)(cvt_pk(f, 0.f) & 0xffffu); }
; template <bool FINAL>
; DI void lru_unit(KA a, int l, int unit, LAS unsigned char* lds) {
;     ...
; #pragma unroll 8
;         for (int t = 0; t < 64; ++t) {
;             const float xv = bf2f(xr[t * 64 + lane]);
;             const float xcv = cb + cw0 * xm3 + cw1 * xm2 + cw2 * xm1 + cw3 * xv;
;             xc[t * 72 + lane] = (t < nvalid) ? f2bf(xcv) : (bf16_t)0;
;             xm3 = xm2; xm2 = xm1; xm1 = xv;
;             if (FINAL && lastc && t >= nvalid - 3 && t < nvalid) cout[(size_t)(t - (nvalid - 3)) * DLRU] = xv;
;         }
.LBB0_968:
	s_addk_i32 s11, 0x400
	s_addk_i32 s23, 0x480
	s_add_i32 s24, s25, 1
	s_cmp_eq_u32 s24, s88
	v_mov_b32_e32 v8, v7
	s_cbranch_scc1 .LBB0_1001
